# attention-probability (P7 softmax epilogue) stores carry the nt hint: 64 MB written in a short store-heavy phase and consumed two phases later
# speedup vs baseline: 1.0053x; 1.0053x over previous
; #define EPI_FOR_ROWS for (int ai = 0; ai < 2; ++ai) _Pragma("unroll") for (int m = 0; m < 4; ++m)
; __device__ __forceinline__ u32x4 pack8(const f32x4 a, const f32x4 b) { u32x4 w; w.x = cvt_pk_bf16(a[0], a[1]); w.y = cvt_pk_bf16(a[2], a[3]); w.z = cvt_pk_bf16(b[0], b[1]); w.w = cvt_pk_bf16(b[2], b[3]); return w; }
;     __device__ __forceinline__ void operator()(f32x4 (&acc)[2][2][4][2], const Unit& u, int wr, int wc, int fr_, int fq_, LAS unsigned char* ldsx) const {
;     ...
;         EPI_FOR_ROWS {
;             const int rl = ai * HALF + wr * 64 + m * 16 + fr;
;             const f32x2 a = X[rl * 4 + 0], b = X[rl * 4 + 1], c = X[rl * 4 + 2], d = X[rl * 4 + 3];
;             const float M = fmaxf(fmaxf(a.x, b.x), fmaxf(c.x, d.x));
;             const float Lsum = a.y * __expf(a.x - M) + b.y * __expf(b.x - M) + c.y * __expf(c.x - M) + d.y * __expf(d.x - M);
;             const float sc = __expf(mx[ai][m] - M) * __builtin_amdgcn_rcpf(Lsum);
;             if (u.nvalid >= 0 ? rl < u.nvalid : rl >= 256 + u.nvalid) {
;                 const size_t row = (size_t)u.row0 + rl;
; #pragma unroll
;                 for (int bj = 0; bj < 2; ++bj) *(u32x4*)(P + row * DM + u.col0 + bj * HALF + wc * 32 + 8 * fq) = pack8(acc[ai][bj][m][0] * sc, acc[ai][bj][m][1] * sc);
;             }
;             asm volatile("" ::: "memory");
;         }
.LBB0_1044:
	v_lshlrev_b32_e32 v58, 3, v173
	v_ashrrev_i32_e32 v59, 31, v58
	s_and_saveexec_b64 s[10:11], s[70:71]
	s_cbranch_execz .LBB0_1046
	s_waitcnt lgkmcnt(0)
	v_max_f32_e32 v17, v2, v2
	v_max_f32_e32 v33, v0, v0
	v_max_f32_e32 v17, v33, v17
	v_max3_f32 v17, v4, v6, v17
	v_sub_f32_e32 v6, v6, v17
	v_sub_f32_e32 v4, v4, v17
	v_mul_f32_e32 v6, 0x3fb8aa3b, v6
	v_mul_f32_e32 v4, 0x3fb8aa3b, v4
	v_exp_f32_e32 v6, v6
	v_sub_f32_e32 v0, v0, v17
	v_exp_f32_e32 v4, v4
	v_mul_f32_e32 v0, 0x3fb8aa3b, v0
	v_sub_f32_e32 v2, v2, v17
	v_exp_f32_e32 v0, v0
	v_mul_f32_e32 v2, 0x3fb8aa3b, v2
	v_exp_f32_e32 v2, v2
	v_mul_f32_e32 v6, v7, v6
	v_fmac_f32_e32 v6, v5, v4
	v_fmac_f32_e32 v6, v1, v0
	v_sub_f32_e32 v0, v158, v17
	v_fmac_f32_e32 v6, v3, v2
	v_mul_f32_e32 v0, 0x3fb8aa3b, v0
	v_exp_f32_e32 v0, v0
	v_rcp_f32_e32 v1, v6
	s_ashr_i32 s17, s16, 31
	v_ashrrev_i32_e32 v95, 31, v94
	s_ashr_i32 s1, s0, 31
	v_mul_f32_e32 v4, v0, v1
	v_lshl_add_u64 v[0:1], v[94:95], 0, s[16:17]
	v_lshlrev_b64 v[6:7], 11, v[0:1]
	v_lshl_add_u64 v[6:7], s[74:75], 0, v[6:7]
	v_lshl_add_u64 v[6:7], s[0:1], 1, v[6:7]
	s_lshl_b32 s18, s90, 1
	v_pk_mul_f32 v[2:3], v[152:153], v[4:5] op_sel_hi:[1,0]
	v_pk_mul_f32 v[0:1], v[148:149], v[4:5] op_sel_hi:[1,0]
	v_lshl_add_u64 v[6:7], v[6:7], 0, s[18:19]
	v_pk_mul_f32 v[148:149], v[162:163], v[4:5] op_sel_hi:[1,0]
	v_pk_mul_f32 v[152:153], v[156:157], v[4:5] op_sel_hi:[1,0]
	v_cvt_pk_bf16_f32 v0, v0, v1
	v_cvt_pk_bf16_f32 v1, v2, v3
	v_cvt_pk_bf16_f32 v3, v148, v149
	v_lshl_add_u64 v[6:7], v[58:59], 1, v[6:7]
	v_cvt_pk_bf16_f32 v2, v152, v153
	global_store_dwordx4 v[6:7], v[0:3], off nt
	s_nop 1
	v_pk_mul_f32 v[2:3], v[150:151], v[4:5] op_sel_hi:[1,0]
	v_pk_mul_f32 v[0:1], v[146:147], v[4:5] op_sel_hi:[1,0]
	v_pk_mul_f32 v[146:147], v[160:161], v[4:5] op_sel_hi:[1,0]
	v_pk_mul_f32 v[4:5], v[154:155], v[4:5] op_sel_hi:[1,0]
	v_cvt_pk_bf16_f32 v0, v0, v1
	v_cvt_pk_bf16_f32 v1, v2, v3
	v_cvt_pk_bf16_f32 v3, v146, v147
	s_nop 0
	v_cvt_pk_bf16_f32 v2, v4, v5
	global_store_dwordx4 v[6:7], v[0:3], off offset:256 nt

; #define EPI_FOR_ROWS for (int ai = 0; ai < 2; ++ai) _Pragma("unroll") for (int m = 0; m < 4; ++m)
; __device__ __forceinline__ u32x4 pack8(const f32x4 a, const f32x4 b) { u32x4 w; w.x = cvt_pk_bf16(a[0], a[1]); w.y = cvt_pk_bf16(a[2], a[3]); w.z = cvt_pk_bf16(b[0], b[1]); w.w = cvt_pk_bf16(b[2], b[3]); return w; }
;     __device__ __forceinline__ void operator()(f32x4 (&acc)[2][2][4][2], const Unit& u, int wr, int wc, int fr_, int fq_, LAS unsigned char* ldsx) const {
;     ...
;         EPI_FOR_ROWS {
;             const int rl = ai * HALF + wr * 64 + m * 16 + fr;
;             const f32x2 a = X[rl * 4 + 0], b = X[rl * 4 + 1], c = X[rl * 4 + 2], d = X[rl * 4 + 3];
;             const float M = fmaxf(fmaxf(a.x, b.x), fmaxf(c.x, d.x));
;             const float Lsum = a.y * __expf(a.x - M) + b.y * __expf(b.x - M) + c.y * __expf(c.x - M) + d.y * __expf(d.x - M);
;             const float sc = __expf(mx[ai][m] - M) * __builtin_amdgcn_rcpf(Lsum);
;             if (u.nvalid >= 0 ? rl < u.nvalid : rl >= 256 + u.nvalid) {
;                 const size_t row = (size_t)u.row0 + rl;
; #pragma unroll
;                 for (int bj = 0; bj < 2; ++bj) *(u32x4*)(P + row * DM + u.col0 + bj * HALF + wc * 32 + 8 * fq) = pack8(acc[ai][bj][m][0] * sc, acc[ai][bj][m][1] * sc);
;             }
;             asm volatile("" ::: "memory");
;         }
.LBB0_1050:
	s_and_saveexec_b64 s[40:41], s[70:71]
	s_cbranch_execz .LBB0_1052
	s_waitcnt lgkmcnt(0)
	v_max_f32_e32 v17, v2, v2
	v_max_f32_e32 v33, v0, v0
	v_max_f32_e32 v17, v33, v17
	v_max3_f32 v17, v4, v6, v17
	v_sub_f32_e32 v6, v6, v17
	v_sub_f32_e32 v4, v4, v17
	v_mul_f32_e32 v6, 0x3fb8aa3b, v6
	v_mul_f32_e32 v4, 0x3fb8aa3b, v4
	v_exp_f32_e32 v6, v6
	v_sub_f32_e32 v0, v0, v17
	v_exp_f32_e32 v4, v4
	v_mul_f32_e32 v0, 0x3fb8aa3b, v0
	v_sub_f32_e32 v2, v2, v17
	v_exp_f32_e32 v0, v0
	v_mul_f32_e32 v2, 0x3fb8aa3b, v2
	v_exp_f32_e32 v2, v2
	v_mul_f32_e32 v6, v7, v6
	v_fmac_f32_e32 v6, v5, v4
	v_fmac_f32_e32 v6, v1, v0
	v_sub_f32_e32 v0, v122, v17
	v_fmac_f32_e32 v6, v3, v2
	v_mul_f32_e32 v0, 0x3fb8aa3b, v0
	v_exp_f32_e32 v0, v0
	v_rcp_f32_e32 v1, v6
	s_ashr_i32 s17, s16, 31
	v_ashrrev_i32_e32 v147, 31, v146
	s_ashr_i32 s1, s0, 31
	v_mul_f32_e32 v4, v0, v1
	v_lshl_add_u64 v[0:1], v[146:147], 0, s[16:17]
	v_lshlrev_b64 v[6:7], 11, v[0:1]
	v_lshl_add_u64 v[6:7], s[74:75], 0, v[6:7]
	v_lshl_add_u64 v[6:7], s[0:1], 1, v[6:7]
	s_lshl_b32 s18, s90, 1
	v_pk_mul_f32 v[2:3], v[140:141], v[4:5] op_sel_hi:[1,0]
	v_pk_mul_f32 v[0:1], v[126:127], v[4:5] op_sel_hi:[1,0]
	v_lshl_add_u64 v[6:7], v[6:7], 0, s[18:19]
	v_pk_mul_f32 v[122:123], v[144:145], v[4:5] op_sel_hi:[1,0]
	v_pk_mul_f32 v[126:127], v[138:139], v[4:5] op_sel_hi:[1,0]
	v_cvt_pk_bf16_f32 v0, v0, v1
	v_cvt_pk_bf16_f32 v1, v2, v3
	v_cvt_pk_bf16_f32 v3, v122, v123
	v_lshl_add_u64 v[6:7], v[58:59], 1, v[6:7]
	v_cvt_pk_bf16_f32 v2, v126, v127
	global_store_dwordx4 v[6:7], v[0:3], off nt
	s_nop 1
	v_pk_mul_f32 v[2:3], v[124:125], v[4:5] op_sel_hi:[1,0]
	v_pk_mul_f32 v[0:1], v[120:121], v[4:5] op_sel_hi:[1,0]
	v_pk_mul_f32 v[120:121], v[142:143], v[4:5] op_sel_hi:[1,0]
	v_pk_mul_f32 v[4:5], v[136:137], v[4:5] op_sel_hi:[1,0]
	v_cvt_pk_bf16_f32 v0, v0, v1
	v_cvt_pk_bf16_f32 v1, v2, v3
	v_cvt_pk_bf16_f32 v3, v120, v121
	s_nop 0
	v_cvt_pk_bf16_f32 v2, v4, v5
	global_store_dwordx4 v[6:7], v[0:3], off offset:256 nt

; #define EPI_FOR_ROWS for (int ai = 0; ai < 2; ++ai) _Pragma("unroll") for (int m = 0; m < 4; ++m)
; __device__ __forceinline__ u32x4 pack8(const f32x4 a, const f32x4 b) { u32x4 w; w.x = cvt_pk_bf16(a[0], a[1]); w.y = cvt_pk_bf16(a[2], a[3]); w.z = cvt_pk_bf16(b[0], b[1]); w.w = cvt_pk_bf16(b[2], b[3]); return w; }
;     __device__ __forceinline__ void operator()(f32x4 (&acc)[2][2][4][2], const Unit& u, int wr, int wc, int fr_, int fq_, LAS unsigned char* ldsx) const {
;     ...
;         EPI_FOR_ROWS {
;             const int rl = ai * HALF + wr * 64 + m * 16 + fr;
;             const f32x2 a = X[rl * 4 + 0], b = X[rl * 4 + 1], c = X[rl * 4 + 2], d = X[rl * 4 + 3];
;             const float M = fmaxf(fmaxf(a.x, b.x), fmaxf(c.x, d.x));
;             const float Lsum = a.y * __expf(a.x - M) + b.y * __expf(b.x - M) + c.y * __expf(c.x - M) + d.y * __expf(d.x - M);
;             const float sc = __expf(mx[ai][m] - M) * __builtin_amdgcn_rcpf(Lsum);
;             if (u.nvalid >= 0 ? rl < u.nvalid : rl >= 256 + u.nvalid) {
;                 const size_t row = (size_t)u.row0 + rl;
; #pragma unroll
;                 for (int bj = 0; bj < 2; ++bj) *(u32x4*)(P + row * DM + u.col0 + bj * HALF + wc * 32 + 8 * fq) = pack8(acc[ai][bj][m][0] * sc, acc[ai][bj][m][1] * sc);
;             }
;             asm volatile("" ::: "memory");
;         }
.LBB0_1056:
	s_and_saveexec_b64 s[40:41], s[70:71]
	s_cbranch_execz .LBB0_1058
	s_waitcnt lgkmcnt(0)
	v_max_f32_e32 v17, v2, v2
	v_max_f32_e32 v33, v0, v0
	v_max_f32_e32 v17, v33, v17
	v_max3_f32 v17, v4, v6, v17
	v_sub_f32_e32 v6, v6, v17
	v_sub_f32_e32 v4, v4, v17
	v_mul_f32_e32 v6, 0x3fb8aa3b, v6
	v_mul_f32_e32 v4, 0x3fb8aa3b, v4
	v_exp_f32_e32 v6, v6
	v_sub_f32_e32 v0, v0, v17
	v_exp_f32_e32 v4, v4
	v_mul_f32_e32 v0, 0x3fb8aa3b, v0
	v_sub_f32_e32 v2, v2, v17
	v_exp_f32_e32 v0, v0
	v_mul_f32_e32 v2, 0x3fb8aa3b, v2
	v_exp_f32_e32 v2, v2
	v_mul_f32_e32 v6, v7, v6
	v_fmac_f32_e32 v6, v5, v4
	v_fmac_f32_e32 v6, v1, v0
	v_sub_f32_e32 v0, v104, v17
	v_fmac_f32_e32 v6, v3, v2
	v_mul_f32_e32 v0, 0x3fb8aa3b, v0
	v_exp_f32_e32 v0, v0
	v_rcp_f32_e32 v1, v6
	s_ashr_i32 s17, s16, 31
	v_ashrrev_i32_e32 v121, 31, v120
	s_ashr_i32 s1, s0, 31
	v_mul_f32_e32 v4, v0, v1
	v_lshl_add_u64 v[0:1], v[120:121], 0, s[16:17]
	v_lshlrev_b64 v[6:7], 11, v[0:1]
	v_lshl_add_u64 v[6:7], s[74:75], 0, v[6:7]
	v_lshl_add_u64 v[6:7], s[0:1], 1, v[6:7]
	s_lshl_b32 s18, s90, 1
	v_pk_mul_f32 v[2:3], v[114:115], v[4:5] op_sel_hi:[1,0]
	v_pk_mul_f32 v[0:1], v[108:109], v[4:5] op_sel_hi:[1,0]
	v_lshl_add_u64 v[6:7], v[6:7], 0, s[18:19]
	v_pk_mul_f32 v[104:105], v[118:119], v[4:5] op_sel_hi:[1,0]
	v_pk_mul_f32 v[108:109], v[112:113], v[4:5] op_sel_hi:[1,0]
	v_cvt_pk_bf16_f32 v0, v0, v1
	v_cvt_pk_bf16_f32 v1, v2, v3
	v_cvt_pk_bf16_f32 v3, v104, v105
	v_lshl_add_u64 v[6:7], v[58:59], 1, v[6:7]
	v_cvt_pk_bf16_f32 v2, v108, v109
	global_store_dwordx4 v[6:7], v[0:3], off nt
	s_nop 1
	v_pk_mul_f32 v[2:3], v[106:107], v[4:5] op_sel_hi:[1,0]
	v_pk_mul_f32 v[0:1], v[102:103], v[4:5] op_sel_hi:[1,0]
	v_pk_mul_f32 v[102:103], v[116:117], v[4:5] op_sel_hi:[1,0]
	v_pk_mul_f32 v[4:5], v[110:111], v[4:5] op_sel_hi:[1,0]
	v_cvt_pk_bf16_f32 v0, v0, v1
	v_cvt_pk_bf16_f32 v1, v2, v3
	v_cvt_pk_bf16_f32 v3, v102, v103
	s_nop 0
	v_cvt_pk_bf16_f32 v2, v4, v5
	global_store_dwordx4 v[6:7], v[0:3], off offset:256 nt

; #define EPI_FOR_ROWS for (int ai = 0; ai < 2; ++ai) _Pragma("unroll") for (int m = 0; m < 4; ++m)
; __device__ __forceinline__ u32x4 pack8(const f32x4 a, const f32x4 b) { u32x4 w; w.x = cvt_pk_bf16(a[0], a[1]); w.y = cvt_pk_bf16(a[2], a[3]); w.z = cvt_pk_bf16(b[0], b[1]); w.w = cvt_pk_bf16(b[2], b[3]); return w; }
;     __device__ __forceinline__ void operator()(f32x4 (&acc)[2][2][4][2], const Unit& u, int wr, int wc, int fr_, int fq_, LAS unsigned char* ldsx) const {
;     ...
;         EPI_FOR_ROWS {
;             const int rl = ai * HALF + wr * 64 + m * 16 + fr;
;             const f32x2 a = X[rl * 4 + 0], b = X[rl * 4 + 1], c = X[rl * 4 + 2], d = X[rl * 4 + 3];
;             const float M = fmaxf(fmaxf(a.x, b.x), fmaxf(c.x, d.x));
;             const float Lsum = a.y * __expf(a.x - M) + b.y * __expf(b.x - M) + c.y * __expf(c.x - M) + d.y * __expf(d.x - M);
;             const float sc = __expf(mx[ai][m] - M) * __builtin_amdgcn_rcpf(Lsum);
;             if (u.nvalid >= 0 ? rl < u.nvalid : rl >= 256 + u.nvalid) {
;                 const size_t row = (size_t)u.row0 + rl;
; #pragma unroll
;                 for (int bj = 0; bj < 2; ++bj) *(u32x4*)(P + row * DM + u.col0 + bj * HALF + wc * 32 + 8 * fq) = pack8(acc[ai][bj][m][0] * sc, acc[ai][bj][m][1] * sc);
;             }
;             asm volatile("" ::: "memory");
;         }
.LBB0_1062:
	s_and_saveexec_b64 s[40:41], s[70:71]
	s_cbranch_execz .LBB0_1064
	s_waitcnt lgkmcnt(0)
	v_max_f32_e32 v17, v2, v2
	v_max_f32_e32 v33, v0, v0
	v_max_f32_e32 v17, v33, v17
	v_max3_f32 v17, v4, v6, v17
	v_sub_f32_e32 v6, v6, v17
	v_sub_f32_e32 v4, v4, v17
	v_mul_f32_e32 v6, 0x3fb8aa3b, v6
	v_mul_f32_e32 v4, 0x3fb8aa3b, v4
	v_exp_f32_e32 v6, v6
	v_sub_f32_e32 v0, v0, v17
	v_exp_f32_e32 v4, v4
	v_mul_f32_e32 v0, 0x3fb8aa3b, v0
	v_sub_f32_e32 v2, v2, v17
	v_exp_f32_e32 v0, v0
	v_mul_f32_e32 v2, 0x3fb8aa3b, v2
	v_exp_f32_e32 v2, v2
	v_mul_f32_e32 v6, v7, v6
	v_fmac_f32_e32 v6, v5, v4
	v_fmac_f32_e32 v6, v1, v0
	v_sub_f32_e32 v0, v84, v17
	v_fmac_f32_e32 v6, v3, v2
	v_mul_f32_e32 v0, 0x3fb8aa3b, v0
	v_exp_f32_e32 v0, v0
	v_rcp_f32_e32 v1, v6
	s_ashr_i32 s17, s16, 31
	v_ashrrev_i32_e32 v103, 31, v102
	s_ashr_i32 s1, s0, 31
	v_mul_f32_e32 v4, v0, v1
	v_lshl_add_u64 v[0:1], v[102:103], 0, s[16:17]
	v_lshlrev_b64 v[6:7], 11, v[0:1]
	v_lshl_add_u64 v[6:7], s[74:75], 0, v[6:7]
	v_lshl_add_u64 v[6:7], s[0:1], 1, v[6:7]
	s_lshl_b32 s18, s90, 1
	v_pk_mul_f32 v[2:3], v[96:97], v[4:5] op_sel_hi:[1,0]
	v_pk_mul_f32 v[0:1], v[88:89], v[4:5] op_sel_hi:[1,0]
	v_lshl_add_u64 v[6:7], v[6:7], 0, s[18:19]
	v_pk_mul_f32 v[84:85], v[100:101], v[4:5] op_sel_hi:[1,0]
	v_pk_mul_f32 v[88:89], v[92:93], v[4:5] op_sel_hi:[1,0]
	v_cvt_pk_bf16_f32 v0, v0, v1
	v_cvt_pk_bf16_f32 v1, v2, v3
	v_cvt_pk_bf16_f32 v3, v84, v85
	v_lshl_add_u64 v[6:7], v[58:59], 1, v[6:7]
	v_cvt_pk_bf16_f32 v2, v88, v89
	global_store_dwordx4 v[6:7], v[0:3], off nt
	s_nop 1
	v_pk_mul_f32 v[2:3], v[86:87], v[4:5] op_sel_hi:[1,0]
	v_pk_mul_f32 v[0:1], v[82:83], v[4:5] op_sel_hi:[1,0]
	v_pk_mul_f32 v[82:83], v[98:99], v[4:5] op_sel_hi:[1,0]
	v_pk_mul_f32 v[4:5], v[90:91], v[4:5] op_sel_hi:[1,0]
	v_cvt_pk_bf16_f32 v0, v0, v1
	v_cvt_pk_bf16_f32 v1, v2, v3
	v_cvt_pk_bf16_f32 v3, v82, v83
	s_nop 0
	v_cvt_pk_bf16_f32 v2, v4, v5
	global_store_dwordx4 v[6:7], v[0:3], off offset:256 nt

; #define EPI_FOR_ROWS for (int ai = 0; ai < 2; ++ai) _Pragma("unroll") for (int m = 0; m < 4; ++m)
; __device__ __forceinline__ u32x4 pack8(const f32x4 a, const f32x4 b) { u32x4 w; w.x = cvt_pk_bf16(a[0], a[1]); w.y = cvt_pk_bf16(a[2], a[3]); w.z = cvt_pk_bf16(b[0], b[1]); w.w = cvt_pk_bf16(b[2], b[3]); return w; }
;     __device__ __forceinline__ void operator()(f32x4 (&acc)[2][2][4][2], const Unit& u, int wr, int wc, int fr_, int fq_, LAS unsigned char* ldsx) const {
;     ...
;         EPI_FOR_ROWS {
;             const int rl = ai * HALF + wr * 64 + m * 16 + fr;
;             const f32x2 a = X[rl * 4 + 0], b = X[rl * 4 + 1], c = X[rl * 4 + 2], d = X[rl * 4 + 3];
;             const float M = fmaxf(fmaxf(a.x, b.x), fmaxf(c.x, d.x));
;             const float Lsum = a.y * __expf(a.x - M) + b.y * __expf(b.x - M) + c.y * __expf(c.x - M) + d.y * __expf(d.x - M);
;             const float sc = __expf(mx[ai][m] - M) * __builtin_amdgcn_rcpf(Lsum);
;             if (u.nvalid >= 0 ? rl < u.nvalid : rl >= 256 + u.nvalid) {
;                 const size_t row = (size_t)u.row0 + rl;
; #pragma unroll
;                 for (int bj = 0; bj < 2; ++bj) *(u32x4*)(P + row * DM + u.col0 + bj * HALF + wc * 32 + 8 * fq) = pack8(acc[ai][bj][m][0] * sc, acc[ai][bj][m][1] * sc);
;             }
;             asm volatile("" ::: "memory");
;         }
.LBB0_1068:
	s_and_saveexec_b64 s[40:41], s[70:71]
	s_cbranch_execz .LBB0_1070
	s_waitcnt lgkmcnt(0)
	v_max_f32_e32 v17, v2, v2
	v_max_f32_e32 v33, v0, v0
	v_max_f32_e32 v17, v33, v17
	v_max3_f32 v17, v4, v6, v17
	v_sub_f32_e32 v6, v6, v17
	v_sub_f32_e32 v4, v4, v17
	v_mul_f32_e32 v6, 0x3fb8aa3b, v6
	v_mul_f32_e32 v4, 0x3fb8aa3b, v4
	v_exp_f32_e32 v6, v6
	v_sub_f32_e32 v0, v0, v17
	v_exp_f32_e32 v4, v4
	v_mul_f32_e32 v0, 0x3fb8aa3b, v0
	v_sub_f32_e32 v2, v2, v17
	v_exp_f32_e32 v0, v0
	v_mul_f32_e32 v2, 0x3fb8aa3b, v2
	v_exp_f32_e32 v2, v2
	v_mul_f32_e32 v6, v7, v6
	v_fmac_f32_e32 v6, v5, v4
	v_fmac_f32_e32 v6, v1, v0
	v_sub_f32_e32 v0, v66, v17
	v_fmac_f32_e32 v6, v3, v2
	v_mul_f32_e32 v0, 0x3fb8aa3b, v0
	v_exp_f32_e32 v0, v0
	v_rcp_f32_e32 v1, v6
	s_ashr_i32 s17, s16, 31
	v_ashrrev_i32_e32 v83, 31, v82
	s_ashr_i32 s1, s0, 31
	v_mul_f32_e32 v4, v0, v1
	v_lshl_add_u64 v[0:1], v[82:83], 0, s[16:17]
	v_lshlrev_b64 v[6:7], 11, v[0:1]
	v_lshl_add_u64 v[6:7], s[74:75], 0, v[6:7]
	v_lshl_add_u64 v[6:7], s[0:1], 1, v[6:7]
	s_lshl_b32 s18, s90, 1
	v_pk_mul_f32 v[2:3], v[76:77], v[4:5] op_sel_hi:[1,0]
	v_pk_mul_f32 v[0:1], v[70:71], v[4:5] op_sel_hi:[1,0]
	v_lshl_add_u64 v[6:7], v[6:7], 0, s[18:19]
	v_pk_mul_f32 v[66:67], v[80:81], v[4:5] op_sel_hi:[1,0]
	v_pk_mul_f32 v[70:71], v[74:75], v[4:5] op_sel_hi:[1,0]
	v_cvt_pk_bf16_f32 v0, v0, v1
	v_cvt_pk_bf16_f32 v1, v2, v3
	v_cvt_pk_bf16_f32 v3, v66, v67
	v_lshl_add_u64 v[6:7], v[58:59], 1, v[6:7]
	v_cvt_pk_bf16_f32 v2, v70, v71
	global_store_dwordx4 v[6:7], v[0:3], off nt
	s_nop 1
	v_pk_mul_f32 v[2:3], v[68:69], v[4:5] op_sel_hi:[1,0]
	v_pk_mul_f32 v[0:1], v[64:65], v[4:5] op_sel_hi:[1,0]
	v_pk_mul_f32 v[64:65], v[78:79], v[4:5] op_sel_hi:[1,0]
	v_pk_mul_f32 v[4:5], v[72:73], v[4:5] op_sel_hi:[1,0]
	v_cvt_pk_bf16_f32 v0, v0, v1
	v_cvt_pk_bf16_f32 v1, v2, v3
	v_cvt_pk_bf16_f32 v3, v64, v65
	s_nop 0
	v_cvt_pk_bf16_f32 v2, v4, v5
	global_store_dwordx4 v[6:7], v[0:3], off offset:256 nt

; #define EPI_FOR_ROWS for (int ai = 0; ai < 2; ++ai) _Pragma("unroll") for (int m = 0; m < 4; ++m)
; __device__ __forceinline__ u32x4 pack8(const f32x4 a, const f32x4 b) { u32x4 w; w.x = cvt_pk_bf16(a[0], a[1]); w.y = cvt_pk_bf16(a[2], a[3]); w.z = cvt_pk_bf16(b[0], b[1]); w.w = cvt_pk_bf16(b[2], b[3]); return w; }
;     __device__ __forceinline__ void operator()(f32x4 (&acc)[2][2][4][2], const Unit& u, int wr, int wc, int fr_, int fq_, LAS unsigned char* ldsx) const {
;     ...
;         EPI_FOR_ROWS {
;             const int rl = ai * HALF + wr * 64 + m * 16 + fr;
;             const f32x2 a = X[rl * 4 + 0], b = X[rl * 4 + 1], c = X[rl * 4 + 2], d = X[rl * 4 + 3];
;             const float M = fmaxf(fmaxf(a.x, b.x), fmaxf(c.x, d.x));
;             const float Lsum = a.y * __expf(a.x - M) + b.y * __expf(b.x - M) + c.y * __expf(c.x - M) + d.y * __expf(d.x - M);
;             const float sc = __expf(mx[ai][m] - M) * __builtin_amdgcn_rcpf(Lsum);
;             if (u.nvalid >= 0 ? rl < u.nvalid : rl >= 256 + u.nvalid) {
;                 const size_t row = (size_t)u.row0 + rl;
; #pragma unroll
;                 for (int bj = 0; bj < 2; ++bj) *(u32x4*)(P + row * DM + u.col0 + bj * HALF + wc * 32 + 8 * fq) = pack8(acc[ai][bj][m][0] * sc, acc[ai][bj][m][1] * sc);
;             }
;             asm volatile("" ::: "memory");
;         }
.LBB0_1074:
	s_and_saveexec_b64 s[40:41], s[70:71]
	s_cbranch_execz .LBB0_1076
	s_waitcnt lgkmcnt(0)
	v_max_f32_e32 v17, v2, v2
	v_max_f32_e32 v33, v0, v0
	v_max_f32_e32 v17, v33, v17
	v_max3_f32 v17, v4, v6, v17
	v_sub_f32_e32 v6, v6, v17
	v_sub_f32_e32 v4, v4, v17
	v_mul_f32_e32 v6, 0x3fb8aa3b, v6
	v_mul_f32_e32 v4, 0x3fb8aa3b, v4
	v_exp_f32_e32 v6, v6
	v_sub_f32_e32 v0, v0, v17
	v_exp_f32_e32 v4, v4
	v_mul_f32_e32 v0, 0x3fb8aa3b, v0
	v_sub_f32_e32 v2, v2, v17
	v_exp_f32_e32 v0, v0
	v_mul_f32_e32 v2, 0x3fb8aa3b, v2
	v_exp_f32_e32 v2, v2
	v_mul_f32_e32 v6, v7, v6
	v_fmac_f32_e32 v6, v5, v4
	v_fmac_f32_e32 v6, v1, v0
	v_sub_f32_e32 v0, v48, v17
	v_fmac_f32_e32 v6, v3, v2
	v_mul_f32_e32 v0, 0x3fb8aa3b, v0
	v_exp_f32_e32 v0, v0
	v_rcp_f32_e32 v1, v6
	s_ashr_i32 s17, s16, 31
	v_ashrrev_i32_e32 v65, 31, v64
	s_ashr_i32 s1, s0, 31
	v_mul_f32_e32 v4, v0, v1
	v_lshl_add_u64 v[0:1], v[64:65], 0, s[16:17]
	v_lshlrev_b64 v[6:7], 11, v[0:1]
	v_lshl_add_u64 v[6:7], s[74:75], 0, v[6:7]
	v_lshl_add_u64 v[6:7], s[0:1], 1, v[6:7]
	s_lshl_b32 s18, s90, 1
	v_pk_mul_f32 v[2:3], v[56:57], v[4:5] op_sel_hi:[1,0]
	v_pk_mul_f32 v[0:1], v[50:51], v[4:5] op_sel_hi:[1,0]
	v_lshl_add_u64 v[6:7], v[6:7], 0, s[18:19]
	v_pk_mul_f32 v[48:49], v[62:63], v[4:5] op_sel_hi:[1,0]
	v_pk_mul_f32 v[50:51], v[54:55], v[4:5] op_sel_hi:[1,0]
	v_cvt_pk_bf16_f32 v0, v0, v1
	v_cvt_pk_bf16_f32 v1, v2, v3
	v_cvt_pk_bf16_f32 v3, v48, v49
	v_lshl_add_u64 v[6:7], v[58:59], 1, v[6:7]
	v_cvt_pk_bf16_f32 v2, v50, v51
	global_store_dwordx4 v[6:7], v[0:3], off nt
	s_nop 1
	v_pk_mul_f32 v[2:3], v[46:47], v[4:5] op_sel_hi:[1,0]
	v_pk_mul_f32 v[0:1], v[44:45], v[4:5] op_sel_hi:[1,0]
	v_pk_mul_f32 v[44:45], v[60:61], v[4:5] op_sel_hi:[1,0]
	v_pk_mul_f32 v[4:5], v[52:53], v[4:5] op_sel_hi:[1,0]
	v_cvt_pk_bf16_f32 v0, v0, v1
	v_cvt_pk_bf16_f32 v1, v2, v3
	v_cvt_pk_bf16_f32 v3, v44, v45
	s_nop 0
	v_cvt_pk_bf16_f32 v2, v4, v5
	global_store_dwordx4 v[6:7], v[0:3], off offset:256 nt

; #define EPI_FOR_ROWS for (int ai = 0; ai < 2; ++ai) _Pragma("unroll") for (int m = 0; m < 4; ++m)
; __device__ __forceinline__ u32x4 pack8(const f32x4 a, const f32x4 b) { u32x4 w; w.x = cvt_pk_bf16(a[0], a[1]); w.y = cvt_pk_bf16(a[2], a[3]); w.z = cvt_pk_bf16(b[0], b[1]); w.w = cvt_pk_bf16(b[2], b[3]); return w; }
;     __device__ __forceinline__ void operator()(f32x4 (&acc)[2][2][4][2], const Unit& u, int wr, int wc, int fr_, int fq_, LAS unsigned char* ldsx) const {
;     ...
;         EPI_FOR_ROWS {
;             const int rl = ai * HALF + wr * 64 + m * 16 + fr;
;             const f32x2 a = X[rl * 4 + 0], b = X[rl * 4 + 1], c = X[rl * 4 + 2], d = X[rl * 4 + 3];
;             const float M = fmaxf(fmaxf(a.x, b.x), fmaxf(c.x, d.x));
;             const float Lsum = a.y * __expf(a.x - M) + b.y * __expf(b.x - M) + c.y * __expf(c.x - M) + d.y * __expf(d.x - M);
;             const float sc = __expf(mx[ai][m] - M) * __builtin_amdgcn_rcpf(Lsum);
;             if (u.nvalid >= 0 ? rl < u.nvalid : rl >= 256 + u.nvalid) {
;                 const size_t row = (size_t)u.row0 + rl;
; #pragma unroll
;                 for (int bj = 0; bj < 2; ++bj) *(u32x4*)(P + row * DM + u.col0 + bj * HALF + wc * 32 + 8 * fq) = pack8(acc[ai][bj][m][0] * sc, acc[ai][bj][m][1] * sc);
;             }
;             asm volatile("" ::: "memory");
;         }
.LBB0_1080:
	s_and_saveexec_b64 s[40:41], s[70:71]
	s_cbranch_execz .LBB0_1082
	s_waitcnt lgkmcnt(0)
	v_max_f32_e32 v17, v2, v2
	v_max_f32_e32 v33, v0, v0
	v_max_f32_e32 v17, v33, v17
	v_max3_f32 v17, v4, v6, v17
	v_sub_f32_e32 v6, v6, v17
	v_sub_f32_e32 v4, v4, v17
	v_mul_f32_e32 v6, 0x3fb8aa3b, v6
	v_mul_f32_e32 v4, 0x3fb8aa3b, v4
	v_exp_f32_e32 v6, v6
	v_sub_f32_e32 v0, v0, v17
	v_exp_f32_e32 v4, v4
	v_mul_f32_e32 v0, 0x3fb8aa3b, v0
	v_sub_f32_e32 v2, v2, v17
	v_exp_f32_e32 v0, v0
	v_mul_f32_e32 v2, 0x3fb8aa3b, v2
	v_exp_f32_e32 v2, v2
	v_mul_f32_e32 v6, v7, v6
	v_fmac_f32_e32 v6, v5, v4
	v_fmac_f32_e32 v6, v1, v0
	v_sub_f32_e32 v0, v32, v17
	v_fmac_f32_e32 v6, v3, v2
	v_mul_f32_e32 v0, 0x3fb8aa3b, v0
	v_exp_f32_e32 v0, v0
	v_rcp_f32_e32 v1, v6
	s_ashr_i32 s17, s16, 31
	v_ashrrev_i32_e32 v45, 31, v44
	s_ashr_i32 s1, s0, 31
	v_mul_f32_e32 v4, v0, v1
	v_lshl_add_u64 v[0:1], v[44:45], 0, s[16:17]
	v_lshlrev_b64 v[6:7], 11, v[0:1]
	v_lshl_add_u64 v[6:7], s[74:75], 0, v[6:7]
	v_lshl_add_u64 v[6:7], s[0:1], 1, v[6:7]
	s_lshl_b32 s18, s90, 1
	v_pk_mul_f32 v[2:3], v[38:39], v[4:5] op_sel_hi:[1,0]
	v_pk_mul_f32 v[0:1], v[30:31], v[4:5] op_sel_hi:[1,0]
	v_lshl_add_u64 v[6:7], v[6:7], 0, s[18:19]
	v_pk_mul_f32 v[30:31], v[42:43], v[4:5] op_sel_hi:[1,0]
	v_pk_mul_f32 v[32:33], v[36:37], v[4:5] op_sel_hi:[1,0]
	v_cvt_pk_bf16_f32 v0, v0, v1
	v_cvt_pk_bf16_f32 v1, v2, v3
	v_cvt_pk_bf16_f32 v3, v30, v31
	v_lshl_add_u64 v[6:7], v[58:59], 1, v[6:7]
	v_cvt_pk_bf16_f32 v2, v32, v33
	global_store_dwordx4 v[6:7], v[0:3], off nt
	s_nop 1
	v_pk_mul_f32 v[2:3], v[28:29], v[4:5] op_sel_hi:[1,0]
	v_pk_mul_f32 v[0:1], v[26:27], v[4:5] op_sel_hi:[1,0]
	v_pk_mul_f32 v[26:27], v[40:41], v[4:5] op_sel_hi:[1,0]
	v_pk_mul_f32 v[4:5], v[34:35], v[4:5] op_sel_hi:[1,0]
	v_cvt_pk_bf16_f32 v0, v0, v1
	v_cvt_pk_bf16_f32 v1, v2, v3
	v_cvt_pk_bf16_f32 v3, v26, v27
	s_nop 0
	v_cvt_pk_bf16_f32 v2, v4, v5
	global_store_dwordx4 v[6:7], v[0:3], off offset:256 nt

; #define EPI_FOR_ROWS for (int ai = 0; ai < 2; ++ai) _Pragma("unroll") for (int m = 0; m < 4; ++m)
; __device__ __forceinline__ u32x4 pack8(const f32x4 a, const f32x4 b) { u32x4 w; w.x = cvt_pk_bf16(a[0], a[1]); w.y = cvt_pk_bf16(a[2], a[3]); w.z = cvt_pk_bf16(b[0], b[1]); w.w = cvt_pk_bf16(b[2], b[3]); return w; }
;     __device__ __forceinline__ void operator()(f32x4 (&acc)[2][2][4][2], const Unit& u, int wr, int wc, int fr_, int fq_, LAS unsigned char* ldsx) const {
;     ...
;         EPI_FOR_ROWS {
;             const int rl = ai * HALF + wr * 64 + m * 16 + fr;
;             const f32x2 a = X[rl * 4 + 0], b = X[rl * 4 + 1], c = X[rl * 4 + 2], d = X[rl * 4 + 3];
;             const float M = fmaxf(fmaxf(a.x, b.x), fmaxf(c.x, d.x));
;             const float Lsum = a.y * __expf(a.x - M) + b.y * __expf(b.x - M) + c.y * __expf(c.x - M) + d.y * __expf(d.x - M);
;             const float sc = __expf(mx[ai][m] - M) * __builtin_amdgcn_rcpf(Lsum);
;             if (u.nvalid >= 0 ? rl < u.nvalid : rl >= 256 + u.nvalid) {
;                 const size_t row = (size_t)u.row0 + rl;
; #pragma unroll
;                 for (int bj = 0; bj < 2; ++bj) *(u32x4*)(P + row * DM + u.col0 + bj * HALF + wc * 32 + 8 * fq) = pack8(acc[ai][bj][m][0] * sc, acc[ai][bj][m][1] * sc);
;             }
;             asm volatile("" ::: "memory");
;         }
.LBB0_1086:
	s_and_saveexec_b64 s[10:11], s[40:41]
	s_cbranch_execz .LBB0_1088
	s_waitcnt lgkmcnt(0)
	v_max_f32_e32 v17, v2, v2
	v_max_f32_e32 v27, v0, v0
	v_max_f32_e32 v17, v27, v17
	v_max3_f32 v17, v4, v6, v17
	v_sub_f32_e32 v6, v6, v17
	v_sub_f32_e32 v4, v4, v17
	v_mul_f32_e32 v6, 0x3fb8aa3b, v6
	v_mul_f32_e32 v4, 0x3fb8aa3b, v4
	v_exp_f32_e32 v6, v6
	v_sub_f32_e32 v0, v0, v17
	v_exp_f32_e32 v4, v4
	v_mul_f32_e32 v0, 0x3fb8aa3b, v0
	v_sub_f32_e32 v2, v2, v17
	v_exp_f32_e32 v0, v0
	v_mul_f32_e32 v2, 0x3fb8aa3b, v2
	v_exp_f32_e32 v2, v2
	v_mul_f32_e32 v6, v7, v6
	v_fmac_f32_e32 v6, v5, v4
	v_fmac_f32_e32 v6, v1, v0
	v_sub_f32_e32 v0, v16, v17
	v_fmac_f32_e32 v6, v3, v2
	v_mul_f32_e32 v0, 0x3fb8aa3b, v0
	v_exp_f32_e32 v0, v0
	v_rcp_f32_e32 v1, v6
	s_ashr_i32 s17, s16, 31
	v_ashrrev_i32_e32 v27, 31, v26
	s_ashr_i32 s1, s0, 31
	v_mul_f32_e32 v4, v0, v1
	v_lshl_add_u64 v[0:1], v[26:27], 0, s[16:17]
	v_lshlrev_b64 v[6:7], 11, v[0:1]
	v_lshl_add_u64 v[6:7], s[74:75], 0, v[6:7]
	v_lshl_add_u64 v[6:7], s[0:1], 1, v[6:7]
	s_lshl_b32 s18, s90, 1
	v_pk_mul_f32 v[2:3], v[20:21], v[4:5] op_sel_hi:[1,0]
	v_pk_mul_f32 v[0:1], v[12:13], v[4:5] op_sel_hi:[1,0]
	v_lshl_add_u64 v[6:7], v[6:7], 0, s[18:19]
	v_pk_mul_f32 v[12:13], v[24:25], v[4:5] op_sel_hi:[1,0]
	v_pk_mul_f32 v[16:17], v[18:19], v[4:5] op_sel_hi:[1,0]
	v_cvt_pk_bf16_f32 v0, v0, v1
	v_cvt_pk_bf16_f32 v1, v2, v3
	v_cvt_pk_bf16_f32 v3, v12, v13
	v_lshl_add_u64 v[6:7], v[58:59], 1, v[6:7]
	v_cvt_pk_bf16_f32 v2, v16, v17
	global_store_dwordx4 v[6:7], v[0:3], off nt
	s_nop 1
	v_pk_mul_f32 v[2:3], v[10:11], v[4:5] op_sel_hi:[1,0]
	v_pk_mul_f32 v[0:1], v[8:9], v[4:5] op_sel_hi:[1,0]
	v_pk_mul_f32 v[8:9], v[22:23], v[4:5] op_sel_hi:[1,0]
	v_pk_mul_f32 v[4:5], v[14:15], v[4:5] op_sel_hi:[1,0]
	v_cvt_pk_bf16_f32 v0, v0, v1
	v_cvt_pk_bf16_f32 v1, v2, v3
	v_cvt_pk_bf16_f32 v3, v8, v9
	s_nop 0
	v_cvt_pk_bf16_f32 v2, v4, v5
	global_store_dwordx4 v[6:7], v[0:3], off offset:256 nt
